# DQK=64 fast path staging addresses: one 64-bit VALU add against an SGPR-pair constant per address instead of add_co/addc pairs (6 fewer VALU per two tiles)
# speedup vs baseline: 1.0044x; 1.0025x over previous
; __device__ __forceinline__ void finishSM(f32x16& p0, f32x16& p1, float alpha, float& l_reg, bf16x8& pa0, bf16x8& pa1, bf16x8& pa2, bf16x8& pa3) {
; #pragma unroll
;   for (int r = 0; r < 16; ++r) p1[r] = __builtin_amdgcn_exp2f(p1[r]);
;   float ps = 0;
; #pragma unroll
;   for (int r = 0; r < 16; ++r) ps += p0[r];
; #pragma unroll
;   for (int r = 0; r < 16; ++r) ps += p1[r];
;   { auto rr = __builtin_amdgcn_permlane32_swap(__float_as_uint(ps), __float_as_uint(ps), false, false);
;     ps = __uint_as_float(rr[0]) + __uint_as_float(rr[1]); }
;   l_reg = l_reg * alpha + ps;
;     ...
;   PK4(p0, 0, pa0); PK4(p0, 8, pa1); PK4(p1, 0, pa2); PK4(p1, 8, pa3);
;     ...
; }
; template <int DQK> __device__ __forceinline__ void qkt(f32x16& p0, f32x16& p1, const char* Ks, const bf16x8* qr, int r32, int hi, const f32x16& negm) {
; #pragma unroll
;   for (int d0 = 0; d0 < DQK / 16; ++d0) { const int cb = (d0 * 16 + hi * 8) * 2;
;     const bf16x8 b0 = *reinterpret_cast<const bf16x8*>(Ks + (DQK == 128 ? KSWZ(r32, cb) : KSWZ64(r32, cb)));
;     const bf16x8 b1 = *reinterpret_cast<const bf16x8*>(Ks + (DQK == 128 ? KSWZ(32 + r32, cb) : KSWZ64(32 + r32, cb)));
;     if (d0 == 0) { p0 = __builtin_amdgcn_mfma_f32_32x32x16_bf16(b0, qr[0], negm, 0, 0, 0); p1 = __builtin_amdgcn_mfma_f32_32x32x16_bf16(b1, qr[0], negm, 0, 0, 0); }
;     else { p0 = __builtin_amdgcn_mfma_f32_32x32x16_bf16(b0, qr[d0], p0, 0, 0, 0); p1 = __builtin_amdgcn_mfma_f32_32x32x16_bf16(b1, qr[d0], p1, 0, 0, 0); } }
; }
; __device__ __forceinline__ int v_st(int k, int c) { const int kk = (k & ~0xC) | ((k & 4) << 1) | ((k & 8) >> 1); return ((kk >> 3) * 4 + (c >> 5)) * 512 + ((kk & 7) * 32 + (c & 31)) * 2; }
; __device__ __forceinline__ int v_rd_base(int lane) { return ((lane & 3) << 3) | (((lane >> 2) & 3) << 6) | (((lane >> 4) & 1) << 5) | (((lane >> 5) & 1) << 8); }
; template <int OFF> __device__ __forceinline__ s16x4 tr_read(int vb) {
;   s16x4 r; asm volatile("ds_read_b64_tr_b16 %0, %1 offset:%2" : "=&v"(r) : "v"(vb), "i"(OFF) : "memory"); return r;
; }
; template <int D0> __device__ __forceinline__ void pv_one(f32x16& od, int vb, bf16x8 pa0, bf16x8 pa1, bf16x8 pa2, bf16x8 pa3) {
;   const s16x4 l0 = tr_read<v_rd_off(D0, 0, 0)>(vb), h0 = tr_read<v_rd_off(D0, 0, 1)>(vb), l1 = tr_read<v_rd_off(D0, 1, 0)>(vb), h1 = tr_read<v_rd_off(D0, 1, 1)>(vb);
.Lcret_f1:
	v_mfma_f32_32x32x16_bf16 v[84:99], v[116:119], v[162:165], v[236:251]
	v_mfma_f32_32x32x16_bf16 v[116:131], v[180:183], v[162:165], v[236:251]
	ds_read_b128 v[180:183], v226 offset:53248
	v_add_f32_e32 v0, 0, v148
	v_add_f32_e32 v0, v178, v0
	v_add_f32_e32 v0, v146, v0
	v_add_f32_e32 v0, v149, v0
	v_add_f32_e32 v0, v144, v0
	v_add_f32_e32 v0, v147, v0
	v_add_f32_e32 v0, v143, v0
	v_add_f32_e32 v0, v145, v0
	v_add_f32_e32 v0, v137, v0
	v_add_f32_e32 v0, v139, v0
	s_waitcnt lgkmcnt(3)
	v_mfma_f32_32x32x16_bf16 v[116:131], v[184:187], v[158:161], v[116:131]
	v_add_f32_e32 v0, v136, v0
	v_add_f32_e32 v0, v138, v0
	v_add_f32_e32 v0, v135, v0
	v_add_f32_e32 v0, v142, v0
	v_add_f32_e32 v0, v140, v0
	v_add_f32_e32 v0, v141, v0
	v_mfma_f32_32x32x16_bf16 v[84:99], v[68:71], v[158:161], v[84:99]
	ds_read_b128 v[184:187], v226 offset:49152
	v_cvt_pk_bf16_f32 v76, v148, v178
	v_cvt_pk_bf16_f32 v77, v146, v149
	v_cvt_pk_bf16_f32 v78, v144, v147
	v_cvt_pk_bf16_f32 v79, v143, v145
	v_lshl_add_u64 v[148:149], v[194:195], 0, s[0:1]
	v_lshl_add_u64 v[196:197], v[192:193], 0, s[0:1]
	s_waitcnt lgkmcnt(2)
	v_mfma_f32_32x32x16_bf16 v[116:131], v[72:75], v[154:157], v[116:131]
	v_cvt_pk_bf16_f32 v80, v137, v139
	v_cvt_pk_bf16_f32 v81, v136, v138
	v_cvt_pk_bf16_f32 v82, v135, v142
	v_cvt_pk_bf16_f32 v83, v140, v141
	s_mov_b64 s[4:5], 0x102b1000
	v_lshl_add_u64 v[132:133], v[148:149], 0, s[4:5]
	v_mfma_f32_32x32x16_bf16 v[84:99], v[206:209], v[154:157], v[84:99]
	ds_read_b64_tr_b16 v[134:135], v223 offset:0
	ds_read_b64_tr_b16 v[136:137], v223 offset:0x800
	ds_read_b64_tr_b16 v[138:139], v223 offset:0x200
	ds_read_b64_tr_b16 v[140:141], v223 offset:0xa00
	ds_read_b64_tr_b16 v[142:143], v223 offset:0x400
	ds_read_b64_tr_b16 v[144:145], v223 offset:0xc00
	ds_read_b64_tr_b16 v[198:199], v223 offset:0x600
	ds_read_b64_tr_b16 v[200:201], v223 offset:0xe00
	v_permlane32_swap_b32_e32 v76, v78
	v_permlane32_swap_b32_e32 v77, v79
	s_mov_b64 s[4:5], 0x102f9000
	v_lshl_add_u64 v[202:203], v[148:149], 0, s[4:5]
	s_waitcnt lgkmcnt(8)
	v_mfma_f32_32x32x16_bf16 v[116:131], v[180:183], v[150:153], v[116:131]
	s_mov_b64 s[4:5], 0x102b0000
	v_lshl_add_u64 v[204:205], v[196:197], 0, s[4:5]
	v_permlane32_swap_b32_e32 v80, v82
	v_permlane32_swap_b32_e32 v81, v83
	v_mfma_f32_32x32x16_bf16 v[84:99], v[184:187], v[150:153], v[84:99]
	global_load_dwordx4 v[178:181], v[132:133], off
	global_load_dwordx4 v[182:185], v[202:203], off
	global_load_dwordx4 v[186:189], v[204:205], off offset:2048
	s_waitcnt lgkmcnt(6)
	v_mfma_f32_32x32x16_bf16 v[50:65], v[76:79], v[134:137], v[50:65]
	ds_read_b64_tr_b16 v[134:135], v223 offset:0x1000
	ds_read_b64_tr_b16 v[136:137], v223 offset:0x1800
	v_exp_f32_e32 v68, v100
	v_exp_f32_e32 v69, v101
	v_add_f32_e32 v0, v68, v0
	s_waitcnt lgkmcnt(6)
	v_mfma_f32_32x32x16_bf16 v[34:49], v[76:79], v[138:141], v[34:49]
	ds_read_b64_tr_b16 v[138:139], v223 offset:0x1200
	ds_read_b64_tr_b16 v[140:141], v223 offset:0x1a00
	v_exp_f32_e32 v70, v102
	v_add_f32_e32 v0, v69, v0
	v_exp_f32_e32 v71, v103
	v_add_f32_e32 v0, v70, v0
	s_waitcnt lgkmcnt(6)
	v_mfma_f32_32x32x16_bf16 v[18:33], v[76:79], v[142:145], v[18:33]
	ds_read_b64_tr_b16 v[142:143], v223 offset:0x1400
	ds_read_b64_tr_b16 v[144:145], v223 offset:0x1c00
	v_exp_f32_e32 v72, v104
	v_add_f32_e32 v0, v71, v0
	v_exp_f32_e32 v73, v105
	v_add_f32_e32 v0, v72, v0
	s_waitcnt lgkmcnt(6)
	v_mfma_f32_32x32x16_bf16 v[2:17], v[76:79], v[198:201], v[2:17]
	ds_read_b64_tr_b16 v[198:199], v223 offset:0x1600
	ds_read_b64_tr_b16 v[200:201], v223 offset:0x1e00
	v_exp_f32_e32 v74, v106
	v_add_f32_e32 v0, v73, v0
	v_exp_f32_e32 v75, v107
	v_add_f32_e32 v0, v74, v0
	v_add_f32_e32 v0, v75, v0
	s_waitcnt lgkmcnt(6)
; #define SBAR() __builtin_amdgcn_sched_barrier(0)
; template <bool FIRST> __device__ __forceinline__ void partialSM(f32x16& p0, f32x16& p1, float& m_reg, float& alpha, f32x16& negm, float c_cur) {
;   float pmax = p0[0];
; #pragma unroll
;   for (int r = 1; r < 16; ++r) pmax = fmaxf(pmax, p0[r]);
; #pragma unroll
;   for (int r = 0; r < 16; ++r) pmax = fmaxf(pmax, p1[r]);
;   { auto rr = __builtin_amdgcn_permlane32_swap(__float_as_uint(pmax), __float_as_uint(pmax), false, false);
;     pmax = fmaxf(__uint_as_float(rr[0]), __uint_as_float(rr[1])); }
;   alpha = 1.f;
;   if (FIRST || !__builtin_expect(__all(pmax <= THR2), 1)) {
;     const float d = FIRST ? pmax : fmaxf(pmax, 0.f); m_reg += d; if (!FIRST) alpha = __builtin_amdgcn_exp2f(-d);
; #pragma unroll
;     for (int r = 0; r < 16; ++r) { p0[r] -= d; p1[r] -= d; }
;     const float nm = c_cur - m_reg;
; #pragma unroll
;     for (int r = 0; r < 16; ++r) negm[r] = nm;
;   }
; #pragma unroll
;   for (int r = 0; r < 16; ++r) p0[r] = __builtin_amdgcn_exp2f(p0[r]);
; }
; __device__ __forceinline__ void finishSM(f32x16& p0, f32x16& p1, float alpha, float& l_reg, bf16x8& pa0, bf16x8& pa1, bf16x8& pa2, bf16x8& pa3) {
; #pragma unroll
;   for (int r = 0; r < 16; ++r) p1[r] = __builtin_amdgcn_exp2f(p1[r]);
;   float ps = 0;
; #pragma unroll
;   for (int r = 0; r < 16; ++r) ps += p0[r];
; #pragma unroll
;   for (int r = 0; r < 16; ++r) ps += p1[r];
;   { auto rr = __builtin_amdgcn_permlane32_swap(__float_as_uint(ps), __float_as_uint(ps), false, false);
;     ps = __uint_as_float(rr[0]) + __uint_as_float(rr[1]); }
;   l_reg = l_reg * alpha + ps;
;     ...
;   PK4(p0, 0, pa0); PK4(p0, 8, pa1); PK4(p1, 0, pa2); PK4(p1, 8, pa3);
;     ...
; }
; template <int D0> __device__ __forceinline__ void pv_one(f32x16& od, int vb, bf16x8 pa0, bf16x8 pa1, bf16x8 pa2, bf16x8 pa3) {
;   const s16x4 l0 = tr_read<v_rd_off(D0, 0, 0)>(vb), h0 = tr_read<v_rd_off(D0, 0, 1)>(vb), l1 = tr_read<v_rd_off(D0, 1, 0)>(vb), h1 = tr_read<v_rd_off(D0, 1, 1)>(vb);
;   const s16x4 l2 = tr_read<v_rd_off(D0, 2, 0)>(vb), h2 = tr_read<v_rd_off(D0, 2, 1)>(vb), l3 = tr_read<v_rd_off(D0, 3, 0)>(vb), h3 = tr_read<v_rd_off(D0, 3, 1)>(vb);
;   asm volatile("s_waitcnt lgkmcnt(0)" ::: "memory"); SBAR();
;     ...
;   od = __builtin_amdgcn_mfma_f32_32x32x16_bf16(pa0, PK(l0, h0), od, 0, 0, 0);
;   od = __builtin_amdgcn_mfma_f32_32x32x16_bf16(pa1, PK(l1, h1), od, 0, 0, 0);
	v_mfma_f32_32x32x16_bf16 v[50:65], v[80:83], v[134:137], v[50:65]
	ds_read_b64_tr_b16 v[134:135], v223 offset:0x2000
	ds_read_b64_tr_b16 v[136:137], v223 offset:0x2800
	v_cvt_pk_bf16_f32 v100, v68, v69
	v_cvt_pk_bf16_f32 v101, v70, v71
	v_cvt_pk_bf16_f32 v102, v72, v73
	v_cvt_pk_bf16_f32 v103, v74, v75
	s_waitcnt lgkmcnt(6)
	v_mfma_f32_32x32x16_bf16 v[34:49], v[80:83], v[138:141], v[34:49]
	ds_read_b64_tr_b16 v[138:139], v223 offset:0x2200
	ds_read_b64_tr_b16 v[140:141], v223 offset:0x2a00
	v_exp_f32_e32 v68, v108
	v_exp_f32_e32 v69, v109
	v_permlane32_swap_b32_e32 v100, v102
	v_permlane32_swap_b32_e32 v101, v103
	s_waitcnt lgkmcnt(6)
	v_mfma_f32_32x32x16_bf16 v[18:33], v[80:83], v[142:145], v[18:33]
	ds_read_b64_tr_b16 v[142:143], v223 offset:0x2400
	ds_read_b64_tr_b16 v[144:145], v223 offset:0x2c00
	v_exp_f32_e32 v70, v110
	v_exp_f32_e32 v71, v111
	v_exp_f32_e32 v72, v112
	s_waitcnt lgkmcnt(6)
	v_mfma_f32_32x32x16_bf16 v[2:17], v[80:83], v[198:201], v[2:17]
	ds_read_b64_tr_b16 v[198:199], v223 offset:0x2600
	ds_read_b64_tr_b16 v[200:201], v223 offset:0x2e00
	v_exp_f32_e32 v73, v113
	v_exp_f32_e32 v74, v114
	v_exp_f32_e32 v75, v115
	s_waitcnt lgkmcnt(6)
	v_mfma_f32_32x32x16_bf16 v[50:65], v[100:103], v[134:137], v[50:65]
	ds_read_b64_tr_b16 v[134:135], v223 offset:0x3000
	ds_read_b64_tr_b16 v[136:137], v223 offset:0x3800
	v_add_f32_e32 v0, v68, v0
	v_add_f32_e32 v0, v69, v0
	v_add_f32_e32 v0, v70, v0
	v_add_f32_e32 v0, v71, v0
	s_waitcnt lgkmcnt(6)
	v_mfma_f32_32x32x16_bf16 v[34:49], v[100:103], v[138:141], v[34:49]
	ds_read_b64_tr_b16 v[138:139], v223 offset:0x3200
	ds_read_b64_tr_b16 v[140:141], v223 offset:0x3a00
	v_add_f32_e32 v0, v72, v0
	v_add_f32_e32 v0, v73, v0
	v_add_f32_e32 v0, v74, v0
	v_add_f32_e32 v0, v75, v0
	v_mov_b32_e32 v231, v0
	s_waitcnt lgkmcnt(6)
	v_mfma_f32_32x32x16_bf16 v[18:33], v[100:103], v[142:145], v[18:33]
	ds_read_b64_tr_b16 v[142:143], v223 offset:0x3400
	ds_read_b64_tr_b16 v[144:145], v223 offset:0x3c00
	v_cvt_pk_bf16_f32 v104, v68, v69
	v_cvt_pk_bf16_f32 v105, v70, v71
	v_cvt_pk_bf16_f32 v106, v72, v73
	v_cvt_pk_bf16_f32 v107, v74, v75
	v_permlane32_swap_b32_e32 v0, v231
	v_max_f32_e32 v132, v84, v85
	v_max3_f32 v132, v132, v86, v87
	s_waitcnt lgkmcnt(6)
	v_mfma_f32_32x32x16_bf16 v[2:17], v[100:103], v[198:201], v[2:17]
	ds_read_b64_tr_b16 v[198:199], v223 offset:0x3600
	ds_read_b64_tr_b16 v[200:201], v223 offset:0x3e00
	v_permlane32_swap_b32_e32 v104, v106
	v_permlane32_swap_b32_e32 v105, v107
	v_max3_f32 v132, v132, v88, v89
	v_max3_f32 v132, v132, v90, v91
	v_max3_f32 v132, v132, v92, v93
	s_waitcnt lgkmcnt(6)
	v_mfma_f32_32x32x16_bf16 v[50:65], v[104:107], v[134:137], v[50:65]
	v_max3_f32 v132, v132, v94, v95
	v_max3_f32 v132, v132, v96, v97
	v_max3_f32 v132, v132, v98, v99
	v_max3_f32 v132, v132, v116, v117
	v_max3_f32 v132, v132, v118, v119
	s_waitcnt lgkmcnt(4)
	v_mfma_f32_32x32x16_bf16 v[34:49], v[104:107], v[138:141], v[34:49]
	v_max3_f32 v132, v132, v120, v121
	v_max3_f32 v132, v132, v122, v123
	v_max3_f32 v132, v132, v124, v125
	v_max3_f32 v132, v132, v126, v127
	v_max3_f32 v132, v132, v128, v129
	v_max3_f32 v132, v132, v130, v131
	v_mov_b32_e32 v133, v132
	s_waitcnt lgkmcnt(2)
	v_mfma_f32_32x32x16_bf16 v[18:33], v[104:107], v[142:145], v[18:33]
	v_permlane32_swap_b32_e32 v132, v133
	v_max_f32_e32 v100, v132, v133
	v_cmp_ge_f32_e32 vcc, s30, v100
	s_waitcnt lgkmcnt(0)
	v_mfma_f32_32x32x16_bf16 v[2:17], v[104:107], v[198:201], v[2:17]
	s_cmp_lg_u64 vcc, exec
	s_cbranch_scc1 .LBB0_255

; __device__ __forceinline__ void finishSM(f32x16& p0, f32x16& p1, float alpha, float& l_reg, bf16x8& pa0, bf16x8& pa1, bf16x8& pa2, bf16x8& pa3) {
; #pragma unroll
;   for (int r = 0; r < 16; ++r) p1[r] = __builtin_amdgcn_exp2f(p1[r]);
;   float ps = 0;
; #pragma unroll
;   for (int r = 0; r < 16; ++r) ps += p0[r];
; #pragma unroll
;   for (int r = 0; r < 16; ++r) ps += p1[r];
;   { auto rr = __builtin_amdgcn_permlane32_swap(__float_as_uint(ps), __float_as_uint(ps), false, false);
;     ps = __uint_as_float(rr[0]) + __uint_as_float(rr[1]); }
;   l_reg = l_reg * alpha + ps;
;     ...
;   PK4(p0, 0, pa0); PK4(p0, 8, pa1); PK4(p1, 0, pa2); PK4(p1, 8, pa3);
;     ...
; }
; template <int DQK> __device__ __forceinline__ void qkt(f32x16& p0, f32x16& p1, const char* Ks, const bf16x8* qr, int r32, int hi, const f32x16& negm) {
; #pragma unroll
;   for (int d0 = 0; d0 < DQK / 16; ++d0) { const int cb = (d0 * 16 + hi * 8) * 2;
;     const bf16x8 b0 = *reinterpret_cast<const bf16x8*>(Ks + (DQK == 128 ? KSWZ(r32, cb) : KSWZ64(r32, cb)));
;     const bf16x8 b1 = *reinterpret_cast<const bf16x8*>(Ks + (DQK == 128 ? KSWZ(32 + r32, cb) : KSWZ64(32 + r32, cb)));
;     if (d0 == 0) { p0 = __builtin_amdgcn_mfma_f32_32x32x16_bf16(b0, qr[0], negm, 0, 0, 0); p1 = __builtin_amdgcn_mfma_f32_32x32x16_bf16(b1, qr[0], negm, 0, 0, 0); }
;     else { p0 = __builtin_amdgcn_mfma_f32_32x32x16_bf16(b0, qr[d0], p0, 0, 0, 0); p1 = __builtin_amdgcn_mfma_f32_32x32x16_bf16(b1, qr[d0], p1, 0, 0, 0); } }
; }
; __device__ __forceinline__ int v_st(int k, int c) { const int kk = (k & ~0xC) | ((k & 4) << 1) | ((k & 8) >> 1); return ((kk >> 3) * 4 + (c >> 5)) * 512 + ((kk & 7) * 32 + (c & 31)) * 2; }
; __device__ __forceinline__ int v_rd_base(int lane) { return ((lane & 3) << 3) | (((lane >> 2) & 3) << 6) | (((lane >> 4) & 1) << 5) | (((lane >> 5) & 1) << 8); }
; template <int OFF> __device__ __forceinline__ s16x4 tr_read(int vb) {
;   s16x4 r; asm volatile("ds_read_b64_tr_b16 %0, %1 offset:%2" : "=&v"(r) : "v"(vb), "i"(OFF) : "memory"); return r;
; }
; template <int D0> __device__ __forceinline__ void pv_one(f32x16& od, int vb, bf16x8 pa0, bf16x8 pa1, bf16x8 pa2, bf16x8 pa3) {
;   const s16x4 l0 = tr_read<v_rd_off(D0, 0, 0)>(vb), h0 = tr_read<v_rd_off(D0, 0, 1)>(vb), l1 = tr_read<v_rd_off(D0, 1, 0)>(vb), h1 = tr_read<v_rd_off(D0, 1, 1)>(vb);
.Lcret_f2:
	v_mfma_f32_32x32x16_bf16 v[68:83], v[100:103], v[162:165], v[236:251]
	v_mfma_f32_32x32x16_bf16 v[100:115], v[84:87], v[162:165], v[236:251]
	ds_read_b128 v[84:87], v226 offset:36864
	v_add_f32_e32 v235, 0, v219
	v_add_f32_e32 v235, v233, v235
	v_add_f32_e32 v235, v209, v235
	v_add_f32_e32 v235, v220, v235
	v_add_f32_e32 v235, v207, v235
	v_add_f32_e32 v235, v218, v235
	v_add_f32_e32 v235, v206, v235
	v_add_f32_e32 v235, v208, v235
	v_add_f32_e32 v235, v203, v235
	v_add_f32_e32 v235, v205, v235
	s_waitcnt lgkmcnt(3)
	v_mfma_f32_32x32x16_bf16 v[100:115], v[88:91], v[158:161], v[100:115]
	v_add_f32_e32 v235, v201, v235
	v_add_f32_e32 v235, v204, v235
	v_add_f32_e32 v235, v199, v235
	v_add_f32_e32 v235, v202, v235
	v_add_f32_e32 v235, v198, v235
	v_add_f32_e32 v235, v200, v235
	v_mfma_f32_32x32x16_bf16 v[68:83], v[134:137], v[158:161], v[68:83]
	ds_read_b128 v[88:91], v226 offset:32768
	v_cvt_pk_bf16_f32 v92, v219, v233
	v_cvt_pk_bf16_f32 v93, v209, v220
	v_cvt_pk_bf16_f32 v94, v207, v218
	v_cvt_pk_bf16_f32 v95, v206, v208
	s_mov_b64 s[98:99], 0x10341000
	v_lshl_add_u64 v[132:133], v[148:149], 0, s[98:99]
	s_waitcnt lgkmcnt(2)
	v_mfma_f32_32x32x16_bf16 v[100:115], v[138:141], v[154:157], v[100:115]
	v_cvt_pk_bf16_f32 v96, v203, v205
	v_cvt_pk_bf16_f32 v97, v201, v204
	s_mov_b64 s[98:99], 0x10389000
	v_lshl_add_u64 v[174:175], v[148:149], 0, s[98:99]
	v_cvt_pk_bf16_f32 v98, v199, v202
	v_cvt_pk_bf16_f32 v99, v198, v200
	v_mfma_f32_32x32x16_bf16 v[68:83], v[142:145], v[154:157], v[68:83]
	ds_read_b64_tr_b16 v[134:135], v211 offset:0
	ds_read_b64_tr_b16 v[136:137], v211 offset:0x800
	ds_read_b64_tr_b16 v[138:139], v211 offset:0x200
	ds_read_b64_tr_b16 v[140:141], v211 offset:0xa00
	ds_read_b64_tr_b16 v[142:143], v211 offset:0x400
	ds_read_b64_tr_b16 v[144:145], v211 offset:0xc00
	ds_read_b64_tr_b16 v[146:147], v211 offset:0x600
	ds_read_b64_tr_b16 v[148:149], v211 offset:0xe00
	v_permlane32_swap_b32_e32 v92, v94
	v_permlane32_swap_b32_e32 v93, v95
	s_mov_b64 s[98:99], 0x10340000
	v_lshl_add_u64 v[176:177], v[196:197], 0, s[98:99]
	s_waitcnt lgkmcnt(8)
	v_mfma_f32_32x32x16_bf16 v[100:115], v[84:87], v[150:153], v[100:115]
	v_permlane32_swap_b32_e32 v96, v98
	v_permlane32_swap_b32_e32 v97, v99
	v_mfma_f32_32x32x16_bf16 v[68:83], v[88:91], v[150:153], v[68:83]
	s_cmp_ge_u32 s4, s28
	s_cbranch_scc1 .Lnold_h2
	global_load_dwordx4 v[166:169], v[132:133], off
	global_load_dwordx4 v[170:173], v[174:175], off
	global_load_dwordx4 v[174:177], v[176:177], off offset:2048
